# attention: row-sum adds moved from QK phase into PV phase gaps (same order), on top of early GEMM barrier
# baseline (speedup 1.0000x reference)
; __device__ __forceinline__ lbraw_t lb_load(const float* lbsrc, int layer, int ch) { lbraw_t r = {0.f, 0.f}; if (layer != 0) { r.x = lbsrc[ch]; r.y = lbsrc[HW + ch]; } return r; }
; template <int PASS>
; __device__ __forceinline__ void hg_load(HgRaw& R, int unit, const bf16* proj, int tid) {
;     const int bh = unit >> 7, c = unit & 127, b = bh >> 3, h = bh & 7; const size_t row0 = (size_t)b * SEQ + (size_t)c * 64; const int k = tid & 127, tg = tid >> 7;
;     const bf16* pz = proj + (row0 + 16 * tg) * INW + h * 128 + k;
; #pragma unroll
;     for (int j = 0; j < 16; ++j) { const unsigned z = pz[(size_t)j * INW + C_FH]; const unsigned q = (PASS == 3) ? pz[(size_t)j * INW + C_QH] : 0u; R.zq[j] = z | (q << 16); }
; #pragma unroll
;     for (int j = 0; j < 8; ++j) { const unsigned a = pz[(size_t)(2 * j) * INW + C_IH], b2 = pz[(size_t)(2 * j + 1) * INW + C_IH]; R.vv[j] = a | (b2 << 16); }
; }
; __global__ void __launch_bounds__(NTHREADS, 2) hymba_fwd(Args args) {
;     ...
;                 HgRaw cur, nxt; const int u0 = vcu < 2048 ? vcu : 2047; hg_load<1>(cur, u0, BIG, tid);
;                 lbraw_t lbc = lb_load(args.in[12], layer, ((u0 >> 7) & 7) * 128 + (tid & 127)), lbn;
;                 for (int u = vcu; u < 2048; u += G) { const int un = u + G < 2048 ? u + G : u; hg_load<1>(nxt, un, BIG, tid); lbn = lb_load(args.in[12], layer, ((un >> 7) & 7) * 128 + (tid & 127));
.LBB0_74:
	s_waitcnt vmcnt(0)
	v_mov_b32_e32 v246, v238
	v_mov_b32_e32 v16, v238
	v_readlane_b32 s4, v252, 27
	v_ashrrev_i32_e32 v0, 3, v16
	v_and_b32_e32 v18, -16, v0
	v_ashrrev_i32_e32 v19, 31, v18
	v_readlane_b32 s5, v252, 28
	s_waitcnt lgkmcnt(0)
	v_and_b32_e32 v21, 0x7f, v16
	v_lshlrev_b32_e32 v220, 1, v21
	v_lshl_add_u64 v[0:1], s[4:5], 0, v[18:19]
	v_readlane_b32 s4, v252, 30
	v_readlane_b32 s5, v252, 31
	s_movk_i32 s64, 0x2000
	s_movk_i32 s65, 0x5000
	s_waitcnt lgkmcnt(1)
	v_mov_b64_e32 v[2:3], s[4:5]
	v_mad_u64_u32 v[2:3], s[4:5], v0, s99, v[2:3]
	v_mov_b32_e32 v0, v3
	v_mad_u64_u32 v[0:1], s[4:5], v1, s99, v[0:1]
	v_mov_b32_e32 v3, v0
	v_lshl_add_u64 v[0:1], v[2:3], 0, v[220:221]
	v_add_co_u32_e32 v2, vcc, s64, v0
	s_mov_b32 s2, 0x13000
	s_nop 0
	v_addc_co_u32_e32 v3, vcc, 0, v1, vcc
	s_waitcnt lgkmcnt(0)
	v_add_co_u32_e32 v4, vcc, s65, v0
	global_load_ushort v56, v[2:3], off
	s_nop 0
	v_addc_co_u32_e32 v5, vcc, 0, v1, vcc
	global_load_ushort v57, v[4:5], off offset:2048
	v_add_co_u32_e32 v4, vcc, s47, v0
	v_readlane_b32 s62, v255, 15
	s_nop 0
	v_addc_co_u32_e32 v5, vcc, 0, v1, vcc
	v_add_co_u32_e32 v6, vcc, s46, v0
	global_load_ushort v55, v[4:5], off
	s_nop 0
	v_addc_co_u32_e32 v7, vcc, 0, v1, vcc
	global_load_ushort v54, v[6:7], off offset:2048
	v_add_co_u32_e32 v6, vcc, s15, v0
	s_add_i32 s4, s62, 12
	s_nop 0
	v_addc_co_u32_e32 v7, vcc, 0, v1, vcc
	v_add_co_u32_e32 v8, vcc, s2, v0
	s_mov_b32 s2, 0x17000
	s_nop 0
	v_addc_co_u32_e32 v9, vcc, 0, v1, vcc
	global_load_ushort v53, v[8:9], off offset:2048
	v_add_co_u32_e32 v8, vcc, s2, v0
	s_mov_b32 s2, 0x1a000
	s_nop 0
	v_addc_co_u32_e32 v9, vcc, 0, v1, vcc
	v_add_co_u32_e32 v10, vcc, s2, v0
	s_mov_b32 s2, 0x1e000
	s_nop 0
	v_addc_co_u32_e32 v11, vcc, 0, v1, vcc
	v_add_co_u32_e32 v22, vcc, s2, v0
	s_mov_b32 s2, 0x21000
	s_nop 0
	v_addc_co_u32_e32 v23, vcc, 0, v1, vcc
	global_load_ushort v52, v[6:7], off
	global_load_ushort v51, v[8:9], off
	global_load_ushort v50, v[10:11], off offset:2048
	global_load_ushort v27, v[22:23], off
	v_add_co_u32_e32 v10, vcc, s2, v0
	s_mov_b32 s2, 0x25000
	s_nop 0
	v_addc_co_u32_e32 v11, vcc, 0, v1, vcc
	v_add_co_u32_e32 v24, vcc, s2, v0
	global_load_ushort v26, v[10:11], off offset:2048
	s_nop 0
	v_addc_co_u32_e32 v25, vcc, 0, v1, vcc
	global_load_ushort v14, v[24:25], off
	v_add_co_u32_e32 v10, vcc, s94, v0
	s_mov_b32 s2, 0x2c000
	s_nop 0
	v_addc_co_u32_e32 v11, vcc, 0, v1, vcc
	v_add_co_u32_e32 v28, vcc, s2, v0
	s_mov_b32 s2, 0x2f000
	s_nop 0
	v_addc_co_u32_e32 v29, vcc, 0, v1, vcc
	global_load_ushort v15, v[10:11], off offset:2048
	global_load_ushort v13, v[28:29], off
	v_add_co_u32_e32 v10, vcc, s2, v0
	s_mov_b32 s2, 0x33000
	s_nop 0
	v_addc_co_u32_e32 v11, vcc, 0, v1, vcc
	v_add_co_u32_e32 v30, vcc, s2, v0
	s_mov_b32 s2, 0x36000
	s_nop 0
	v_addc_co_u32_e32 v31, vcc, 0, v1, vcc
	v_add_co_u32_e32 v32, vcc, s2, v0
	s_movk_i32 s2, 0x6000
	s_nop 0
	v_addc_co_u32_e32 v33, vcc, 0, v1, vcc
	global_load_ushort v12, v[10:11], off offset:2048
	s_cmp_gt_u32 s4, 24
	global_load_ushort v11, v[30:31], off
	global_load_ushort v10, v[32:33], off offset:2048
	s_nop 0
	global_load_ushort v2, v[2:3], off offset:2048
	v_add_co_u32_e32 v32, vcc, s2, v0
	s_mov_b32 s2, 0xd000
	s_nop 0
	v_addc_co_u32_e32 v33, vcc, 0, v1, vcc
	global_load_ushort v3, v[32:33], off
	s_nop 0
	global_load_ushort v4, v[4:5], off offset:2048
	v_add_co_u32_e32 v32, vcc, s2, v0
	s_mov_b32 s2, 0x14000
	s_nop 0
	v_addc_co_u32_e32 v33, vcc, 0, v1, vcc
	global_load_ushort v5, v[32:33], off
	s_nop 0
	global_load_ushort v6, v[6:7], off offset:2048
	v_add_co_u32_e32 v32, vcc, s2, v0
	s_mov_b32 s2, 0x1b000
	s_nop 0
	v_addc_co_u32_e32 v33, vcc, 0, v1, vcc
	global_load_ushort v7, v[32:33], off
	s_nop 0
	global_load_ushort v8, v[8:9], off offset:2048
	v_add_co_u32_e32 v32, vcc, s2, v0
	s_mov_b32 s2, 0x22000
	s_nop 0
	v_addc_co_u32_e32 v33, vcc, 0, v1, vcc
	global_load_ushort v9, v[32:33], off
	global_load_ushort v17, v[22:23], off offset:2048
	v_add_co_u32_e32 v22, vcc, s2, v0
	s_mov_b32 s2, 0x29000
	s_nop 0
	v_addc_co_u32_e32 v23, vcc, 0, v1, vcc
	global_load_ushort v20, v[22:23], off
	s_nop 0
	global_load_ushort v22, v[24:25], off offset:2048
	v_add_co_u32_e32 v24, vcc, s2, v0
	v_mov_b32_e32 v69, 0
	s_nop 0
	v_addc_co_u32_e32 v25, vcc, 0, v1, vcc
	global_load_ushort v23, v[24:25], off
	s_nop 0
	global_load_ushort v24, v[28:29], off offset:2048
	v_add_co_u32_e32 v28, vcc, 0x30000, v0
	s_cselect_b64 s[36:37], -1, 0
	s_nop 0
	v_addc_co_u32_e32 v29, vcc, 0, v1, vcc
	v_add_co_u32_e32 v0, vcc, 0x37000, v0
	global_load_ushort v25, v[28:29], off
	s_nop 0
	global_load_ushort v28, v[30:31], off offset:2048
	v_addc_co_u32_e32 v1, vcc, 0, v1, vcc
	global_load_ushort v29, v[0:1], off
	s_cmp_lt_u32 s4, 25
	v_mov_b32_e32 v72, 0
	s_cbranch_scc1 .LBB0_76
	v_readlane_b32 s4, v252, 29
	v_readlane_b32 s16, v252, 48
	v_mov_b32_e32 v1, v221
	v_or_b32_e32 v0, s4, v21
	v_lshlrev_b32_e32 v0, 2, v0
	v_readlane_b32 s24, v252, 56
	v_readlane_b32 s25, v252, 57
	v_readlane_b32 s17, v252, 49
	v_readlane_b32 s18, v252, 50
	v_lshl_add_u64 v[30:31], s[24:25], 0, v[0:1]
	v_readlane_b32 s19, v252, 51
	v_readlane_b32 s20, v252, 52
	global_load_dword v69, v0, s[24:25]
	v_add_co_u32_e32 v0, vcc, 0x1000, v30
	v_readlane_b32 s21, v252, 53
	s_nop 0
	v_addc_co_u32_e32 v1, vcc, 0, v31, vcc
	global_load_dword v72, v[0:1], off
	v_readlane_b32 s22, v252, 54
	v_readlane_b32 s23, v252, 55
	v_readlane_b32 s26, v252, 58
	v_readlane_b32 s27, v252, 59
	v_readlane_b32 s28, v252, 60
	v_readlane_b32 s29, v252, 61
	v_readlane_b32 s30, v252, 62
	v_readlane_b32 s31, v252, 63

; #define WAIT_BAR(N) asm volatile("s_waitcnt vmcnt(" #N ") lgkmcnt(0)\n\ts_barrier":::"memory")
;   #define DMA_K(t,slot) glds16(ksrc+(long)(t)*KVBLK*PIN,(unsigned)__builtin_amdgcn_readfirstlane(kdst+(slot)))
;   #define DMA_V(t,slot) do{ glds16(vsrc+(long)(t)*KVBLK*PIN,(unsigned)__builtin_amdgcn_readfirstlane(vdst+2*(slot))); glds16(vsrc+(long)(t)*KVBLK*PIN+64,(unsigned)__builtin_amdgcn_readfirstlane(vdst+2*(slot)+SLOTB)); }while(0)
;   #define CMASK(P0,P1,t) do{int jb_=(t)-(NT-4); if(jb_>=0)cmask(P0,P1,jb_,qrel,hi);}while(0)
;   #define START(P0,P1) do{ const float rm=rowmax(P0,P1); resc=false; \
;     { const float dl=rm; mhat=fadd_s(mhat,dl); \
;       _Pragma("unroll") for(int r=0;r<16;++r){P0[r]=fsub_s(P0[r],dl);P1[r]=fsub_s(P1[r],dl);} \
;       _Pragma("unroll") for(int r=0;r<16;++r)negm[r]=-mhat; asm volatile("":"+v"(negm)); } \
;     _Pragma("unroll") for(int r=0;r<16;++r)P0[r]=__builtin_amdgcn_exp2f(P0[r]); }while(0)
;   #define ROT() do{sl_prev=sl_cur;sl_cur=sl_next;sl_next=(sl_next==(NSLOT-1)*SLOTB)?0:sl_next+SLOTB;}while(0)
;   #define CMASK(P0,P1,t) do{}while(0)
;   #define CMASK(P0,P1,t) do{int jb_=(t)-(NT-4); if(jb_>=0)cmask(P0,P1,jb_,qrel,hi);}while(0)
; template<int THRL> __device__ __forceinline__ void attn_unit(int b,int qcol,int kcol,int vcol,int ocol,int qb,const bf16*__restrict__ P,bf16*__restrict__ O,char*shm){
;     ...
;   DMA_K(2,2*SLOTB);
;   WAIT_BAR(4);
;   qkt(pA0,pA1,Kbase,qr,negm,r32,hi);asm volatile("s_nop 15\n\ts_nop 7":"+v"(pA0),"+v"(pA1));CMASK(pA0,pA1,0);
;   START(pA0,pA1);
;   _Pragma("unroll") for(int r=0;r<16;++r)pA1[r]=__builtin_amdgcn_exp2f(pA1[r]);
;   WAIT_BAR(0);
;   DMA_K(3,0);DMA_V(1,SLOTB);
;   ROT();
;   kload8(kf,kp0+sl_cur);
;   WAIT_BAR(3);
;   s16x4 vlo[8],vhi[8]; u32x4 pw0,pw1,pw2,pw3;
.LBB0_88:
	v_lshlrev_b32_e32 v35, 1, v34
	v_and_b32_e32 v242, 32, v35
	v_lshlrev_b32_e32 v35, 4, v34
	v_and_b32_e32 v35, 0xc0, v35
	v_lshl_or_b32 v243, v232, 8, v35
	v_add_u32_e32 v35, 0, v242
	v_add3_u32 v225, v35, v251, v243
	v_max3_f32 v35, v16, v17, v0
	v_max3_f32 v36, v18, v19, v1
	s_and_b32 s17, s17, 0x3fffffc0
	v_max3_f32 v35, v35, v2, v3
	v_max3_f32 v36, v36, v22, v23
	s_lshl_b32 s17, s17, 2
	v_max3_f32 v35, v35, v20, v21
	v_max3_f32 v36, v36, v6, v7
	s_add_i32 s20, s23, 0x100
	v_max3_f32 v35, v35, v4, v5
	v_max3_f32 v36, v36, v26, v27
	s_add_i32 s17, s17, 0
	v_max3_f32 v35, v35, v24, v25
	v_max3_f32 v36, v36, v10, v11
	s_add_i32 s17, s17, 0x12000
	v_max3_f32 v35, v35, v8, v9
	v_max3_f32 v36, v36, v30, v31
	s_lshr_b32 s20, s20, 6
	v_max3_f32 v35, v35, v28, v29
	v_max3_f32 v36, v36, v14, v15
	s_cmp_lg_u32 0, -1
	v_max3_f32 v35, v35, v12, v13
	s_mov_b64 s[28:29], 0xe0000
	v_max_f32_e32 v35, v35, v36
	s_mov_b32 s27, 1
	v_mov_b32_e32 v36, v35
	s_nop 1
	v_permlane32_swap_b32_e32 v35, v36
	v_max_f32_e32 v35, v35, v36
	s_mov_b32 s25, 0
	v_add_f32_e32 v223, v221, v35
	v_sub_f32_e32 v0, v0, v35
	v_sub_f32_e32 v1, v1, v35
	v_sub_f32_e32 v16, v16, v35
	v_sub_f32_e32 v17, v17, v35
	v_sub_f32_e32 v18, v18, v35
	s_nop 0
	v_xor_b32_e32 v64, 0x80000000, v223
	v_mov_b32_e32 v65, v64
	v_mov_b32_e32 v66, v64
	v_mov_b32_e32 v67, v64
	v_mov_b32_e32 v68, v64
	v_mov_b32_e32 v69, v64
	v_mov_b32_e32 v70, v64
	v_mov_b32_e32 v71, v64
	v_mov_b32_e32 v72, v64
	v_mov_b32_e32 v73, v64
	v_mov_b32_e32 v74, v64
	v_mov_b32_e32 v75, v64
	v_mov_b32_e32 v76, v64
	v_mov_b32_e32 v77, v64
	v_mov_b32_e32 v78, v64
	v_mov_b32_e32 v79, v64
	s_waitcnt vmcnt(0) lgkmcnt(0)
	s_barrier
	v_exp_f32_e32 v80, v0
	v_exp_f32_e32 v81, v1
	v_lshl_add_u64 v[0:1], v[230:231], 0, s[96:97]
	s_mov_b32 s24, m0
	s_mov_b32 m0, s18
	s_nop 0
	global_load_lds_dwordx4 v[0:1], off
	s_mov_b32 m0, s24
	s_cselect_b32 s24, 0, 0
	s_add_i32 s21, s24, s21
	v_lshl_add_u64 v[0:1], v[32:33], 0, s[28:29]
	s_add_i32 s24, s21, 0xa000
	s_mov_b32 s26, m0
	s_mov_b32 m0, s24
	s_nop 0
	global_load_lds_dwordx4 v[0:1], off
	s_mov_b32 m0, s26
	s_mov_b64 s[28:29], 0xe0080
	v_lshl_add_u64 v[0:1], v[32:33], 0, s[28:29]
	s_add_i32 s21, s21, 0xc000
	s_mov_b32 s24, m0
	s_mov_b32 m0, s21
	s_nop 0
	global_load_lds_dwordx4 v[0:1], off
	s_mov_b32 m0, s24
	ds_read_b128 v[204:207], v224 offset:8192
	ds_read_b128 v[200:203], v224 offset:8704
	ds_read_b128 v[196:199], v224 offset:10240
	ds_read_b128 v[192:195], v224 offset:10752
	ds_read_b128 v[188:191], v224 offset:12288
	ds_read_b128 v[184:187], v224 offset:12800
	ds_read_b128 v[180:183], v224 offset:14336
	ds_read_b128 v[176:179], v224 offset:14848
	v_sub_f32_e32 v2, v2, v35
	v_sub_f32_e32 v19, v19, v35
	v_sub_f32_e32 v3, v3, v35
	v_sub_f32_e32 v20, v20, v35
	v_sub_f32_e32 v4, v4, v35
	v_sub_f32_e32 v21, v21, v35
	v_sub_f32_e32 v5, v5, v35
	v_sub_f32_e32 v22, v22, v35
	v_sub_f32_e32 v6, v6, v35
	v_sub_f32_e32 v23, v23, v35
	v_sub_f32_e32 v7, v7, v35
	v_sub_f32_e32 v24, v24, v35
	v_sub_f32_e32 v8, v8, v35
	v_sub_f32_e32 v25, v25, v35
	v_sub_f32_e32 v9, v9, v35
	v_sub_f32_e32 v26, v26, v35
	v_sub_f32_e32 v10, v10, v35
	v_sub_f32_e32 v27, v27, v35
	v_sub_f32_e32 v11, v11, v35
	v_sub_f32_e32 v28, v28, v35
	v_sub_f32_e32 v12, v12, v35
	v_sub_f32_e32 v29, v29, v35
	v_sub_f32_e32 v13, v13, v35
	v_sub_f32_e32 v30, v30, v35
	v_sub_f32_e32 v14, v14, v35
	v_sub_f32_e32 v31, v31, v35
	v_sub_f32_e32 v15, v15, v35
	v_exp_f32_e32 v96, v16
	v_exp_f32_e32 v97, v17
	v_exp_f32_e32 v98, v18
	v_exp_f32_e32 v99, v19
	v_exp_f32_e32 v100, v20
	v_exp_f32_e32 v101, v21
	v_exp_f32_e32 v102, v22
	v_exp_f32_e32 v103, v23
	v_exp_f32_e32 v104, v24
	v_exp_f32_e32 v105, v25
	v_exp_f32_e32 v106, v26
	v_exp_f32_e32 v107, v27
	v_exp_f32_e32 v108, v28
	v_exp_f32_e32 v109, v29
	v_exp_f32_e32 v110, v30
	v_exp_f32_e32 v111, v31
	v_exp_f32_e32 v82, v2
	v_exp_f32_e32 v83, v3
	v_exp_f32_e32 v84, v4
	v_exp_f32_e32 v85, v5
	v_exp_f32_e32 v86, v6
	v_exp_f32_e32 v87, v7
	v_exp_f32_e32 v88, v8
	v_exp_f32_e32 v89, v9
	v_exp_f32_e32 v90, v10
	v_exp_f32_e32 v91, v11
	v_exp_f32_e32 v92, v12
	v_exp_f32_e32 v93, v13
	v_exp_f32_e32 v94, v14
	v_exp_f32_e32 v95, v15
	s_waitcnt vmcnt(3) lgkmcnt(0)
	s_barrier
	v_and_b32_e32 v0, 3, v34
	s_andn2_b64 vcc, exec, s[4:5]
	v_cmp_gt_u32_e64 s[4:5], 32, v247
	v_lshlrev_b32_e32 v226, 4, v232
	v_lshl_add_u32 v245, v248, 2, s17
	v_lshlrev_b32_e32 v212, 4, v0
	s_cbranch_vccnz .LBB0_104
	v_mov_b32_e32 v213, v221
	v_lshl_add_u64 v[0:1], s[6:7], 1, v[212:213]
	v_lshl_add_u64 v[0:1], v[0:1], 0, v[220:221]
	v_mov_b32_e32 v32, v221
	v_mov_b32_e32 v33, v221
	v_mov_b32_e32 v46, v221
	v_mov_b32_e32 v47, v221
	v_lshl_add_u64 v[214:215], s[64:65], 0, v[0:1]
	v_mov_b32_e32 v34, v221
	v_mov_b32_e32 v35, v221
	v_mov_b32_e32 v36, v221
	v_mov_b32_e32 v37, v221
	v_mov_b32_e32 v38, v221
	v_mov_b32_e32 v39, v221
	v_mov_b32_e32 v40, v221
	v_mov_b32_e32 v41, v221
	v_mov_b32_e32 v42, v221
	v_mov_b32_e32 v43, v221
	v_mov_b32_e32 v44, v221
	v_mov_b32_e32 v45, v221
	v_mov_b64_e32 v[62:63], v[46:47]
	v_mov_b64_e32 v[16:17], v[32:33]
	v_mov_b64_e32 v[0:1], v[32:33]
	s_mov_b32 s28, 0
	s_movk_i32 s25, 0x4000
	s_movk_i32 s27, 0x2000
	v_mov_b32_e32 v227, 0
	s_mov_b32 s26, 6
	s_mov_b64 s[36:37], 0
	v_mov_b64_e32 v[60:61], v[44:45]
	v_mov_b64_e32 v[58:59], v[42:43]
	v_mov_b64_e32 v[56:57], v[40:41]
	v_mov_b64_e32 v[54:55], v[38:39]
	v_mov_b64_e32 v[52:53], v[36:37]
	v_mov_b64_e32 v[50:51], v[34:35]
	v_mov_b64_e32 v[48:49], v[32:33]
	v_mov_b64_e32 v[18:19], v[34:35]
	v_mov_b64_e32 v[20:21], v[36:37]
	v_mov_b64_e32 v[22:23], v[38:39]
	v_mov_b64_e32 v[24:25], v[40:41]
	v_mov_b64_e32 v[26:27], v[42:43]
	v_mov_b64_e32 v[28:29], v[44:45]
	v_mov_b64_e32 v[30:31], v[46:47]
	v_mov_b64_e32 v[2:3], v[34:35]
	v_mov_b64_e32 v[4:5], v[36:37]
	v_mov_b64_e32 v[6:7], v[38:39]
	v_mov_b64_e32 v[8:9], v[40:41]
	v_mov_b64_e32 v[10:11], v[42:43]
	v_mov_b64_e32 v[12:13], v[44:45]
	v_mov_b64_e32 v[14:15], v[46:47]
	v_add_f32_e32 v246, v96, v97
	v_add_f32_e32 v246, v98, v246
	v_add_f32_e32 v246, v99, v246
	v_add_f32_e32 v246, v100, v246
	v_add_f32_e32 v246, v101, v246
	v_add_f32_e32 v246, v102, v246
	v_add_f32_e32 v246, v103, v246
	v_add_f32_e32 v246, v104, v246
	v_add_f32_e32 v246, v105, v246
	v_add_f32_e32 v246, v106, v246
	v_add_f32_e32 v246, v107, v246
	v_add_f32_e32 v246, v108, v246
	v_add_f32_e32 v246, v109, v246
	v_add_f32_e32 v246, v110, v246
	v_add_f32_e32 v246, v111, v246
	v_add_f32_e32 v246, v80, v246
	v_add_f32_e32 v246, v81, v246
	v_add_f32_e32 v246, v82, v246
	v_add_f32_e32 v246, v83, v246
	v_add_f32_e32 v246, v84, v246
	v_add_f32_e32 v246, v85, v246
	v_add_f32_e32 v246, v86, v246
	v_add_f32_e32 v246, v87, v246
	v_add_f32_e32 v246, v88, v246
	v_add_f32_e32 v246, v89, v246
	v_add_f32_e32 v246, v90, v246
	v_add_f32_e32 v246, v91, v246
	v_add_f32_e32 v246, v92, v246
	v_add_f32_e32 v246, v93, v246
	v_add_f32_e32 v246, v94, v246
	v_add_f32_e32 v246, v95, v246
.LBB0_90:
	v_add_f32_e32 v227, v227, v246
	s_lshl_b32 s21, s28, 1
	v_add_u32_e32 v213, s21, v225
	ds_read_b64_tr_b16 v[208:209], v213 offset:24576
	ds_read_b64_tr_b16 v[210:211], v213 offset:25088
	s_waitcnt lgkmcnt(9)
	v_mfma_f32_32x32x16_bf16 v[128:143], v[204:207], v[172:175], v[64:79]
	v_cvt_pk_bf16_f32 v164, v96, v97
	v_cvt_pk_bf16_f32 v165, v98, v99
	ds_read_b64_tr_b16 v[204:205], v213 offset:28672
	ds_read_b64_tr_b16 v[206:207], v213 offset:29184
	s_waitcnt lgkmcnt(10)
	v_mfma_f32_32x32x16_bf16 v[112:127], v[200:203], v[172:175], v[64:79]
	v_cvt_pk_bf16_f32 v166, v100, v101
	v_cvt_pk_bf16_f32 v167, v102, v103
	ds_read_b64_tr_b16 v[96:97], v213 offset:25600
	ds_read_b64_tr_b16 v[98:99], v213 offset:26112
	s_waitcnt lgkmcnt(11)
	v_mfma_f32_32x32x16_bf16 v[128:143], v[196:199], v[168:171], v[128:143]
	v_cvt_pk_bf16_f32 v156, v104, v105
	v_cvt_pk_bf16_f32 v157, v106, v107
	ds_read_b64_tr_b16 v[100:101], v213 offset:29696
	ds_read_b64_tr_b16 v[102:103], v213 offset:30208
	s_waitcnt lgkmcnt(12)
	v_mfma_f32_32x32x16_bf16 v[112:127], v[192:195], v[168:171], v[112:127]
	v_cvt_pk_bf16_f32 v158, v108, v109
	v_cvt_pk_bf16_f32 v159, v110, v111
	ds_read_b64_tr_b16 v[104:105], v213 offset:26624
	ds_read_b64_tr_b16 v[106:107], v213 offset:27136
	s_waitcnt lgkmcnt(13)
	v_mfma_f32_32x32x16_bf16 v[128:143], v[188:191], v[160:163], v[128:143]
	v_cvt_pk_bf16_f32 v148, v80, v81
	v_cvt_pk_bf16_f32 v149, v82, v83
	ds_read_b64_tr_b16 v[108:109], v213 offset:30720
	ds_read_b64_tr_b16 v[110:111], v213 offset:31232
	s_waitcnt lgkmcnt(14)
	v_mfma_f32_32x32x16_bf16 v[112:127], v[184:187], v[160:163], v[112:127]
	v_cvt_pk_bf16_f32 v150, v84, v85
	v_cvt_pk_bf16_f32 v151, v86, v87
	ds_read_b64_tr_b16 v[84:85], v213 offset:27648
	ds_read_b64_tr_b16 v[86:87], v213 offset:28160
	s_waitcnt lgkmcnt(14)
	v_mfma_f32_32x32x16_bf16 v[128:143], v[180:183], v[152:155], v[128:143]
	v_cvt_pk_bf16_f32 v144, v88, v89
	v_cvt_pk_bf16_f32 v145, v90, v91
	ds_read_b64_tr_b16 v[88:89], v213 offset:31744
	ds_read_b64_tr_b16 v[90:91], v213 offset:32256
	v_mfma_f32_32x32x16_bf16 v[112:127], v[176:179], v[152:155], v[112:127]
	v_cvt_pk_bf16_f32 v146, v92, v93
	v_cvt_pk_bf16_f32 v147, v94, v95
	v_lshl_add_u64 v[218:219], v[230:231], 0, s[36:37]
	v_lshl_add_u64 v[80:81], v[218:219], 0, s[92:93]
	s_add_i32 s21, s27, s18
	v_lshl_add_u64 v[216:217], v[214:215], 0, s[36:37]
	s_mov_b32 s24, m0
	s_mov_b32 m0, s21
	s_nop 0
	global_load_lds_dwordx4 v[80:81], off
	s_mov_b32 m0, s24
	v_lshl_add_u64 v[80:81], v[216:217], 0, s[0:1]
	s_lshl_b32 s21, s25, 1
	s_add_i32 s21, s21, s19
	s_mov_b32 s24, m0
	s_mov_b32 m0, s21
	s_nop 0
	global_load_lds_dwordx4 v[80:81], off
	s_mov_b32 m0, s24
	v_lshl_add_u64 v[80:81], v[216:217], 0, s[68:69]
	s_addk_i32 s21, 0x2000
	s_mov_b32 s24, m0
	s_mov_b32 m0, s21
	s_nop 0
	global_load_lds_dwordx4 v[80:81], off
	s_mov_b32 m0, s24
	v_max_f32_e32 v80, v129, v129
	v_max_f32_e32 v81, v128, v128
	v_max_f32_e32 v80, v81, v80
	v_max3_f32 v81, v130, v131, v113
	v_max3_f32 v80, v80, v112, v114
	v_max3_f32 v80, v80, v115, v132
	v_max3_f32 v81, v81, v134, v135
	v_max3_f32 v80, v80, v133, v116
	v_max3_f32 v81, v81, v118, v119
	v_max3_f32 v80, v80, v117, v136
	v_max3_f32 v81, v81, v138, v139
	v_max3_f32 v80, v80, v137, v120
	v_max3_f32 v81, v81, v122, v123
	v_max3_f32 v80, v80, v121, v140
	v_max3_f32 v81, v81, v142, v143
	v_max3_f32 v80, v80, v141, v124
	v_max3_f32 v81, v81, v126, v127
	v_max3_f32 v80, v80, v125, v81
	v_mov_b32_e32 v81, v80
	s_nop 1
	v_permlane32_swap_b32_e32 v80, v81
	v_max_f32_e32 v81, v81, v81
	v_max_f32_e32 v80, v80, v80
	v_max_f32_e32 v80, v80, v81
	v_cmp_lt_f32_e32 vcc, s74, v80
	s_cmp_lg_u64 vcc, 0
	s_cselect_b64 s[38:39], -1, 0
	s_cbranch_vccnz .LBB0_98
.LBB0_91:
	s_waitcnt lgkmcnt(14)
	v_mfma_f32_32x32x16_bf16 v[32:47], v[164:167], v[208:211], v[32:47]
	v_exp_f32_e32 v128, v128
	v_exp_f32_e32 v129, v129
	ds_read_b64_tr_b16 v[92:93], v213 offset:32768
	ds_read_b64_tr_b16 v[94:95], v213 offset:33280
	s_waitcnt lgkmcnt(14)
	v_mfma_f32_32x32x16_bf16 v[48:63], v[164:167], v[204:207], v[48:63]
	v_add_f32_e32 v246, v128, v129
	v_exp_f32_e32 v130, v130
	v_exp_f32_e32 v131, v131
	ds_read_b64_tr_b16 v[204:205], v213 offset:36864
	ds_read_b64_tr_b16 v[206:207], v213 offset:37376
	v_add_u32_e32 v176, s25, v224
	ds_read_b128 v[80:83], v176
	ds_read_b128 v[196:199], v176 offset:512
	s_waitcnt lgkmcnt(14)
	v_mfma_f32_32x32x16_bf16 v[32:47], v[156:159], v[96:99], v[32:47]
	v_add_f32_e32 v246, v130, v246
	v_add_f32_e32 v246, v131, v246
	v_exp_f32_e32 v132, v132
	v_exp_f32_e32 v133, v133
	ds_read_b64_tr_b16 v[96:97], v213 offset:33792
	ds_read_b64_tr_b16 v[98:99], v213 offset:34304
	ds_read_b128 v[200:203], v176 offset:2048
	ds_read_b128 v[192:195], v176 offset:2560
	v_mfma_f32_32x32x16_bf16 v[48:63], v[156:159], v[100:103], v[48:63]
	v_add_f32_e32 v246, v132, v246
	v_add_f32_e32 v246, v133, v246
	v_exp_f32_e32 v134, v134
	v_exp_f32_e32 v135, v135
	ds_read_b64_tr_b16 v[100:101], v213 offset:37888
	ds_read_b64_tr_b16 v[102:103], v213 offset:38400
	ds_read_b128 v[188:191], v176 offset:4096
	ds_read_b128 v[184:187], v176 offset:4608
	s_waitcnt lgkmcnt(14)
	v_mfma_f32_32x32x16_bf16 v[32:47], v[148:151], v[104:107], v[32:47]
	v_add_f32_e32 v246, v134, v246
	v_add_f32_e32 v246, v135, v246
	v_exp_f32_e32 v136, v136
	v_exp_f32_e32 v137, v137
	ds_read_b64_tr_b16 v[104:105], v213 offset:34816
	ds_read_b64_tr_b16 v[106:107], v213 offset:35328
	ds_read_b128 v[180:183], v176 offset:6144
	ds_read_b128 v[176:179], v176 offset:6656
	v_mfma_f32_32x32x16_bf16 v[48:63], v[148:151], v[108:111], v[48:63]
	v_add_f32_e32 v246, v136, v246
	v_add_f32_e32 v246, v137, v246
	v_exp_f32_e32 v138, v138
	v_exp_f32_e32 v139, v139
	ds_read_b64_tr_b16 v[108:109], v213 offset:38912
	ds_read_b64_tr_b16 v[110:111], v213 offset:39424
	v_mfma_f32_32x32x16_bf16 v[32:47], v[144:147], v[84:87], v[32:47]
	v_add_f32_e32 v246, v138, v246
	v_add_f32_e32 v246, v139, v246
	v_exp_f32_e32 v140, v140
	v_exp_f32_e32 v141, v141
	ds_read_b64_tr_b16 v[84:85], v213 offset:35840
	ds_read_b64_tr_b16 v[86:87], v213 offset:36352
	v_mfma_f32_32x32x16_bf16 v[48:63], v[144:147], v[88:91], v[48:63]
	v_add_f32_e32 v246, v140, v246
	v_add_f32_e32 v246, v141, v246
	v_exp_f32_e32 v142, v142
	v_exp_f32_e32 v143, v143
	ds_read_b64_tr_b16 v[88:89], v213 offset:39936
	ds_read_b64_tr_b16 v[90:91], v213 offset:40448
	s_waitcnt lgkmcnt(14)
	v_mfma_f32_32x32x16_bf16 v[16:31], v[164:167], v[92:95], v[16:31]
	v_add_f32_e32 v246, v142, v246
	v_add_f32_e32 v246, v143, v246
	v_exp_f32_e32 v112, v112
	v_exp_f32_e32 v113, v113
	v_mfma_f32_32x32x16_bf16 v[0:15], v[164:167], v[204:207], v[0:15]
	v_add_f32_e32 v246, v112, v246
	v_add_f32_e32 v246, v113, v246
	v_exp_f32_e32 v114, v114
	v_exp_f32_e32 v115, v115
	v_mfma_f32_32x32x16_bf16 v[16:31], v[156:159], v[96:99], v[16:31]
	v_add_f32_e32 v246, v114, v246
	v_add_f32_e32 v246, v115, v246
	v_exp_f32_e32 v116, v116
	v_exp_f32_e32 v117, v117
	s_waitcnt lgkmcnt(12)
	v_mfma_f32_32x32x16_bf16 v[0:15], v[156:159], v[100:103], v[0:15]
	v_add_f32_e32 v246, v116, v246
	v_add_f32_e32 v246, v117, v246
	v_exp_f32_e32 v118, v118
	v_exp_f32_e32 v119, v119
	s_waitcnt lgkmcnt(8)
	v_mfma_f32_32x32x16_bf16 v[16:31], v[148:151], v[104:107], v[16:31]
	v_add_f32_e32 v246, v118, v246
	v_add_f32_e32 v246, v119, v246
	v_exp_f32_e32 v120, v120
	v_exp_f32_e32 v121, v121
	s_waitcnt lgkmcnt(4)
	v_mfma_f32_32x32x16_bf16 v[0:15], v[148:151], v[108:111], v[0:15]
	v_add_f32_e32 v246, v120, v246
	v_add_f32_e32 v246, v121, v246
	v_exp_f32_e32 v122, v122
	v_exp_f32_e32 v123, v123
	s_waitcnt lgkmcnt(2)
	v_mfma_f32_32x32x16_bf16 v[16:31], v[144:147], v[84:87], v[16:31]
	v_add_f32_e32 v246, v122, v246
	v_add_f32_e32 v246, v123, v246
	v_exp_f32_e32 v124, v124
	v_exp_f32_e32 v125, v125
	s_waitcnt lgkmcnt(0)
	v_mfma_f32_32x32x16_bf16 v[0:15], v[144:147], v[88:91], v[0:15]
	v_add_f32_e32 v246, v124, v246
	v_add_f32_e32 v246, v125, v246
	v_exp_f32_e32 v126, v126
	v_exp_f32_e32 v127, v127
	s_waitcnt vmcnt(3) lgkmcnt(0)
	s_barrier
	v_add_f32_e32 v246, v126, v246
	v_add_f32_e32 v246, v127, v246
	s_andn2_b64 vcc, exec, s[38:39]
	v_add_u32_e32 v213, s17, v226
	s_cbranch_vccnz .LBB0_93
	s_waitcnt lgkmcnt(0)
	ds_read_b128 v[84:87], v213 offset:96
	ds_read_b128 v[88:91], v213 offset:64
	ds_read_b128 v[92:95], v213 offset:32
	ds_read_b128 v[96:99], v213
	s_waitcnt lgkmcnt(3)
	v_pk_mul_f32 v[44:45], v[44:45], v[84:85]
	s_waitcnt lgkmcnt(2)
	v_pk_mul_f32 v[40:41], v[40:41], v[88:89]
	s_waitcnt lgkmcnt(1)
	v_pk_mul_f32 v[36:37], v[36:37], v[92:93]
	v_pk_mul_f32 v[46:47], v[46:47], v[86:87]
	v_pk_mul_f32 v[42:43], v[42:43], v[90:91]
	v_pk_mul_f32 v[38:39], v[38:39], v[94:95]
	s_waitcnt lgkmcnt(0)
	v_pk_mul_f32 v[34:35], v[34:35], v[98:99]
	v_pk_mul_f32 v[32:33], v[32:33], v[96:97]
	v_pk_mul_f32 v[60:61], v[60:61], v[84:85]
	v_pk_mul_f32 v[56:57], v[56:57], v[88:89]
	v_pk_mul_f32 v[52:53], v[52:53], v[92:93]
	v_pk_mul_f32 v[62:63], v[62:63], v[86:87]
	v_pk_mul_f32 v[58:59], v[58:59], v[90:91]
	v_pk_mul_f32 v[54:55], v[54:55], v[94:95]
	v_pk_mul_f32 v[50:51], v[50:51], v[98:99]
	v_pk_mul_f32 v[48:49], v[48:49], v[96:97]
	v_pk_mul_f32 v[28:29], v[28:29], v[84:85]
	v_pk_mul_f32 v[24:25], v[24:25], v[88:89]
	v_pk_mul_f32 v[20:21], v[20:21], v[92:93]
	v_pk_mul_f32 v[30:31], v[30:31], v[86:87]
	v_pk_mul_f32 v[26:27], v[26:27], v[90:91]
	v_pk_mul_f32 v[22:23], v[22:23], v[94:95]
	v_pk_mul_f32 v[18:19], v[18:19], v[98:99]
	v_pk_mul_f32 v[16:17], v[16:17], v[96:97]
	v_pk_mul_f32 v[12:13], v[12:13], v[84:85]
	v_pk_mul_f32 v[8:9], v[8:9], v[88:89]
	v_pk_mul_f32 v[4:5], v[4:5], v[92:93]
	v_pk_mul_f32 v[14:15], v[14:15], v[86:87]
	v_pk_mul_f32 v[10:11], v[10:11], v[90:91]
	v_pk_mul_f32 v[6:7], v[6:7], v[94:95]
	v_pk_mul_f32 v[2:3], v[2:3], v[98:99]
	v_pk_mul_f32 v[0:1], v[0:1], v[96:97]
.LBB0_93:
	v_add_f32_e32 v227, v227, v246
	s_add_i32 s21, s25, 0x2000
	s_cmpk_lg_i32 s25, 0x4000
	s_cselect_b32 s21, s21, 0
	s_lshl_b32 s24, s27, 1
	v_add_u32_e32 v228, s24, v225
	ds_read_b64_tr_b16 v[204:205], v228 offset:24576
	ds_read_b64_tr_b16 v[206:207], v228 offset:25088
	v_mfma_f32_32x32x16_bf16 v[96:111], v[80:83], v[172:175], v[64:79]
	v_cvt_pk_bf16_f32 v164, v128, v129
	v_cvt_pk_bf16_f32 v165, v130, v131
	ds_read_b64_tr_b16 v[208:209], v228 offset:28672
	ds_read_b64_tr_b16 v[210:211], v228 offset:29184
	v_mfma_f32_32x32x16_bf16 v[80:95], v[196:199], v[172:175], v[64:79]
	v_cvt_pk_bf16_f32 v166, v132, v133
	v_cvt_pk_bf16_f32 v167, v134, v135
	ds_read_b64_tr_b16 v[128:129], v228 offset:25600
	ds_read_b64_tr_b16 v[130:131], v228 offset:26112
	v_mfma_f32_32x32x16_bf16 v[96:111], v[200:203], v[168:171], v[96:111]
	v_cvt_pk_bf16_f32 v156, v136, v137
	v_cvt_pk_bf16_f32 v157, v138, v139
	ds_read_b64_tr_b16 v[132:133], v228 offset:29696
	ds_read_b64_tr_b16 v[134:135], v228 offset:30208
	v_mfma_f32_32x32x16_bf16 v[80:95], v[192:195], v[168:171], v[80:95]
	v_cvt_pk_bf16_f32 v158, v140, v141
	v_cvt_pk_bf16_f32 v159, v142, v143
	ds_read_b64_tr_b16 v[136:137], v228 offset:26624
	ds_read_b64_tr_b16 v[138:139], v228 offset:27136
	v_mfma_f32_32x32x16_bf16 v[96:111], v[188:191], v[160:163], v[96:111]
	v_cvt_pk_bf16_f32 v148, v112, v113
	v_cvt_pk_bf16_f32 v149, v114, v115
	ds_read_b64_tr_b16 v[112:113], v228 offset:30720
	ds_read_b64_tr_b16 v[114:115], v228 offset:31232
	v_mfma_f32_32x32x16_bf16 v[80:95], v[184:187], v[160:163], v[80:95]
	v_cvt_pk_bf16_f32 v150, v116, v117
	v_cvt_pk_bf16_f32 v151, v118, v119
	ds_read_b64_tr_b16 v[116:117], v228 offset:27648
	ds_read_b64_tr_b16 v[118:119], v228 offset:28160
	v_mfma_f32_32x32x16_bf16 v[96:111], v[180:183], v[152:155], v[96:111]
	v_cvt_pk_bf16_f32 v144, v120, v121
	v_cvt_pk_bf16_f32 v145, v122, v123
	ds_read_b64_tr_b16 v[120:121], v228 offset:31744
	ds_read_b64_tr_b16 v[122:123], v228 offset:32256
	v_mfma_f32_32x32x16_bf16 v[80:95], v[176:179], v[152:155], v[80:95]
	v_cvt_pk_bf16_f32 v146, v124, v125
	v_cvt_pk_bf16_f32 v147, v126, v127
	s_mov_b64 s[28:29], 0x460000
	v_lshl_add_u64 v[124:125], v[218:219], 0, s[28:29]
	s_add_i32 s24, s25, s18
	s_mov_b64 s[28:29], 0x12aa1000
	s_mov_b32 s27, m0
	s_mov_b32 m0, s24
	s_nop 0
	global_load_lds_dwordx4 v[124:125], off
	s_mov_b32 m0, s27
	v_lshl_add_u64 v[124:125], v[216:217], 0, s[28:29]
	s_lshl_b32 s24, s21, 1
	s_mov_b64 s[28:29], 0x12aa1080
	s_add_i32 s24, s24, s19
	s_mov_b32 s27, m0
	s_mov_b32 m0, s24
	s_nop 0
	global_load_lds_dwordx4 v[124:125], off
	s_mov_b32 m0, s27
	v_lshl_add_u64 v[124:125], v[216:217], 0, s[28:29]
	s_addk_i32 s24, 0x2000
	s_mov_b32 s27, m0
	s_mov_b32 m0, s24
	s_nop 0
	global_load_lds_dwordx4 v[124:125], off
	s_mov_b32 m0, s27
	v_max_f32_e32 v124, v97, v97
	v_max_f32_e32 v125, v96, v96
	v_max_f32_e32 v124, v125, v124
	v_max3_f32 v125, v98, v99, v81
	v_max3_f32 v124, v124, v80, v82
	v_max3_f32 v124, v124, v83, v100
	v_max3_f32 v125, v125, v102, v103
	v_max3_f32 v124, v124, v101, v84
	v_max3_f32 v125, v125, v86, v87
	v_max3_f32 v124, v124, v85, v104
	v_max3_f32 v125, v125, v106, v107
	v_max3_f32 v124, v124, v105, v88
	v_max3_f32 v125, v125, v90, v91
	v_max3_f32 v124, v124, v89, v108
	v_max3_f32 v125, v125, v110, v111
	v_max3_f32 v124, v124, v109, v92
	v_max3_f32 v125, v125, v94, v95
	v_max3_f32 v124, v124, v93, v125
	v_mov_b32_e32 v125, v124
	s_nop 1
	v_permlane32_swap_b32_e32 v124, v125
	v_max_f32_e32 v125, v125, v125
	v_max_f32_e32 v124, v124, v124
	v_max_f32_e32 v124, v124, v125
	v_cmp_lt_f32_e32 vcc, s74, v124
	s_cmp_lg_u64 vcc, 0
	s_cselect_b64 s[38:39], -1, 0
	s_cbranch_vccnz .LBB0_101
.LBB0_94:
	s_waitcnt lgkmcnt(14)
	v_mfma_f32_32x32x16_bf16 v[32:47], v[164:167], v[204:207], v[32:47]
	v_exp_f32_e32 v96, v96
	v_exp_f32_e32 v97, v97
	ds_read_b64_tr_b16 v[124:125], v228 offset:32768
	ds_read_b64_tr_b16 v[126:127], v228 offset:33280
	s_waitcnt lgkmcnt(14)
	v_mfma_f32_32x32x16_bf16 v[48:63], v[164:167], v[208:211], v[48:63]
	v_add_f32_e32 v246, v96, v97
	v_exp_f32_e32 v98, v98
	v_exp_f32_e32 v99, v99
	ds_read_b64_tr_b16 v[140:141], v228 offset:36864
	ds_read_b64_tr_b16 v[142:143], v228 offset:37376
	v_add_u32_e32 v176, s21, v224
	ds_read_b128 v[204:207], v176
	ds_read_b128 v[200:203], v176 offset:512
	s_waitcnt lgkmcnt(14)
	v_mfma_f32_32x32x16_bf16 v[32:47], v[156:159], v[128:131], v[32:47]
	v_add_f32_e32 v246, v98, v246
	v_add_f32_e32 v246, v99, v246
	v_exp_f32_e32 v100, v100
	v_exp_f32_e32 v101, v101
	ds_read_b64_tr_b16 v[128:129], v228 offset:33792
	ds_read_b64_tr_b16 v[130:131], v228 offset:34304
	ds_read_b128 v[196:199], v176 offset:2048
	ds_read_b128 v[192:195], v176 offset:2560
	v_mfma_f32_32x32x16_bf16 v[48:63], v[156:159], v[132:135], v[48:63]
	v_add_f32_e32 v246, v100, v246
	v_add_f32_e32 v246, v101, v246
	v_exp_f32_e32 v102, v102
	v_exp_f32_e32 v103, v103
	ds_read_b64_tr_b16 v[132:133], v228 offset:37888
	ds_read_b64_tr_b16 v[134:135], v228 offset:38400
	ds_read_b128 v[188:191], v176 offset:4096
	ds_read_b128 v[184:187], v176 offset:4608
	s_waitcnt lgkmcnt(14)
	v_mfma_f32_32x32x16_bf16 v[32:47], v[148:151], v[136:139], v[32:47]
	v_add_f32_e32 v246, v102, v246
	v_add_f32_e32 v246, v103, v246
	v_exp_f32_e32 v104, v104
	v_exp_f32_e32 v105, v105
	ds_read_b64_tr_b16 v[136:137], v228 offset:34816
	ds_read_b64_tr_b16 v[138:139], v228 offset:35328
	ds_read_b128 v[180:183], v176 offset:6144
	ds_read_b128 v[176:179], v176 offset:6656
	v_mfma_f32_32x32x16_bf16 v[48:63], v[148:151], v[112:115], v[48:63]
	v_add_f32_e32 v246, v104, v246
	v_add_f32_e32 v246, v105, v246
	v_exp_f32_e32 v106, v106
	v_exp_f32_e32 v107, v107
	ds_read_b64_tr_b16 v[112:113], v228 offset:38912
	ds_read_b64_tr_b16 v[114:115], v228 offset:39424
	v_mfma_f32_32x32x16_bf16 v[32:47], v[144:147], v[116:119], v[32:47]
	v_add_f32_e32 v246, v106, v246
	v_add_f32_e32 v246, v107, v246
	v_exp_f32_e32 v108, v108
	v_exp_f32_e32 v109, v109
	ds_read_b64_tr_b16 v[116:117], v228 offset:35840
	ds_read_b64_tr_b16 v[118:119], v228 offset:36352
	v_mfma_f32_32x32x16_bf16 v[48:63], v[144:147], v[120:123], v[48:63]
	v_add_f32_e32 v246, v108, v246
	v_add_f32_e32 v246, v109, v246
	v_exp_f32_e32 v110, v110
	v_exp_f32_e32 v111, v111
	ds_read_b64_tr_b16 v[120:121], v228 offset:39936
	ds_read_b64_tr_b16 v[122:123], v228 offset:40448
	s_waitcnt lgkmcnt(14)
	v_mfma_f32_32x32x16_bf16 v[16:31], v[164:167], v[124:127], v[16:31]
	v_add_f32_e32 v246, v110, v246
	v_add_f32_e32 v246, v111, v246
	v_exp_f32_e32 v80, v80
	v_exp_f32_e32 v81, v81
	v_mfma_f32_32x32x16_bf16 v[0:15], v[164:167], v[140:143], v[0:15]
	v_add_f32_e32 v246, v80, v246
	v_add_f32_e32 v246, v81, v246
	v_exp_f32_e32 v82, v82
	v_exp_f32_e32 v83, v83
	v_mfma_f32_32x32x16_bf16 v[16:31], v[156:159], v[128:131], v[16:31]
	v_add_f32_e32 v246, v82, v246
	v_add_f32_e32 v246, v83, v246
	v_exp_f32_e32 v84, v84
	v_exp_f32_e32 v85, v85
	s_waitcnt lgkmcnt(12)
	v_mfma_f32_32x32x16_bf16 v[0:15], v[156:159], v[132:135], v[0:15]
	v_add_f32_e32 v246, v84, v246
	v_add_f32_e32 v246, v85, v246
	v_exp_f32_e32 v86, v86
	v_exp_f32_e32 v87, v87
	s_waitcnt lgkmcnt(8)
	v_mfma_f32_32x32x16_bf16 v[16:31], v[148:151], v[136:139], v[16:31]
	v_add_f32_e32 v246, v86, v246
	v_add_f32_e32 v246, v87, v246
	v_exp_f32_e32 v88, v88
	v_exp_f32_e32 v89, v89
	s_waitcnt lgkmcnt(4)
	v_mfma_f32_32x32x16_bf16 v[0:15], v[148:151], v[112:115], v[0:15]
	v_add_f32_e32 v246, v88, v246
	v_add_f32_e32 v246, v89, v246
	v_exp_f32_e32 v90, v90
	v_exp_f32_e32 v91, v91
	s_waitcnt lgkmcnt(2)
	v_mfma_f32_32x32x16_bf16 v[16:31], v[144:147], v[116:119], v[16:31]
	v_add_f32_e32 v246, v90, v246
	v_add_f32_e32 v246, v91, v246
	v_exp_f32_e32 v92, v92
	v_exp_f32_e32 v93, v93
	s_waitcnt lgkmcnt(0)
	v_mfma_f32_32x32x16_bf16 v[0:15], v[144:147], v[120:123], v[0:15]
	v_add_f32_e32 v246, v92, v246
	v_add_f32_e32 v246, v93, v246
	v_exp_f32_e32 v94, v94
	v_exp_f32_e32 v95, v95
	s_waitcnt vmcnt(3) lgkmcnt(0)
	s_barrier
	v_add_f32_e32 v246, v94, v246
	v_add_f32_e32 v246, v95, v246
	s_andn2_b64 vcc, exec, s[38:39]
	s_cbranch_vccnz .LBB0_96
	s_waitcnt lgkmcnt(0)
	ds_read_b128 v[112:115], v213 offset:96
	ds_read_b128 v[116:119], v213 offset:64
	ds_read_b128 v[120:123], v213 offset:32
	ds_read_b128 v[124:127], v213
	s_waitcnt lgkmcnt(3)
	v_pk_mul_f32 v[44:45], v[44:45], v[112:113]
	s_waitcnt lgkmcnt(2)
	v_pk_mul_f32 v[40:41], v[40:41], v[116:117]
	s_waitcnt lgkmcnt(1)
	v_pk_mul_f32 v[36:37], v[36:37], v[120:121]
	v_pk_mul_f32 v[46:47], v[46:47], v[114:115]
	v_pk_mul_f32 v[42:43], v[42:43], v[118:119]
	v_pk_mul_f32 v[38:39], v[38:39], v[122:123]
	s_waitcnt lgkmcnt(0)
	v_pk_mul_f32 v[34:35], v[34:35], v[126:127]
	v_pk_mul_f32 v[32:33], v[32:33], v[124:125]
	v_pk_mul_f32 v[60:61], v[60:61], v[112:113]
	v_pk_mul_f32 v[56:57], v[56:57], v[116:117]
	v_pk_mul_f32 v[52:53], v[52:53], v[120:121]
	v_pk_mul_f32 v[62:63], v[62:63], v[114:115]
	v_pk_mul_f32 v[58:59], v[58:59], v[118:119]
	v_pk_mul_f32 v[54:55], v[54:55], v[122:123]
	v_pk_mul_f32 v[50:51], v[50:51], v[126:127]
	v_pk_mul_f32 v[48:49], v[48:49], v[124:125]
	v_pk_mul_f32 v[28:29], v[28:29], v[112:113]
	v_pk_mul_f32 v[24:25], v[24:25], v[116:117]
	v_pk_mul_f32 v[20:21], v[20:21], v[120:121]
	v_pk_mul_f32 v[30:31], v[30:31], v[114:115]
	v_pk_mul_f32 v[26:27], v[26:27], v[118:119]
	v_pk_mul_f32 v[22:23], v[22:23], v[122:123]
	v_pk_mul_f32 v[18:19], v[18:19], v[126:127]
	v_pk_mul_f32 v[16:17], v[16:17], v[124:125]
	v_pk_mul_f32 v[12:13], v[12:13], v[112:113]
	v_pk_mul_f32 v[8:9], v[8:9], v[116:117]
	v_pk_mul_f32 v[4:5], v[4:5], v[120:121]
	v_pk_mul_f32 v[14:15], v[14:15], v[114:115]
	v_pk_mul_f32 v[10:11], v[10:11], v[118:119]
	v_pk_mul_f32 v[6:7], v[6:7], v[122:123]
	v_pk_mul_f32 v[2:3], v[2:3], v[126:127]
	v_pk_mul_f32 v[0:1], v[0:1], v[124:125]
